# g3: loop-invariant gla_norm_w loads hoisted out of the unit loop, redundant lgkmcnt waits between DPP adds removed
# baseline (speedup 1.0000x reference)
; #define LAS __attribute__((address_space(3)))
; __device__ __forceinline__ void phase_g3(const Args& a, LAS unsigned char* lds, int tid, int lane, int wave) {
;     LAS float* aL = (LAS float*)lds; LAS float* tot = (LAS float*)(lds + 4096); LAS float* part = (LAS float*)(lds + 6144); LAS float* rstdL = (LAS float*)(lds + 8192);
;     LAS bf16* Qs = (LAS bf16*)(lds + 8704); LAS bf16* Ks = (LAS bf16*)(lds + 8704 + 17408); LAS bf16* Ps = (LAS bf16*)(lds + 8704 + 2 * 17408);
;     LAS bf16* Vs = (LAS bf16*)(lds + 52736); LAS bf16* Rs = (LAS bf16*)(lds + 86528);
;     const bf16* proj = (const bf16*)(a.ws + WS_PROJ); const bf16* S = (const bf16*)(a.ws + WS_S); bf16* Y = (bf16*)(a.ws + WS_H);
;     const int d = tid & 127, ig = tid >> 7, r16 = lane & 15, q4 = lane >> 4;
;     GateIn gin; v4u qreg[2], kreg[2], vreg[4], rreg[4];
;     ...
;     if ((int)blockIdx.x < 2048) G3_LOADS((int)blockIdx.x);
;     for (int unit = blockIdx.x; unit < 2048; unit += gridDim.x) {
;     ...
;         for (int nt = 0; nt < 2; ++nt) { const int e = 32 * wave + 16 * nt + r16; const float gw = a.in[I_GNW][e];
.LBB0_421:
	v_mov_b32_e32 v107, 0
	v_and_b32_e32 v55, 0x1c00, v55
	v_add_u32_e32 v148, 0, v55
	v_lshlrev_b32_e32 v106, 1, v54
	v_lshlrev_b32_e32 v54, 1, v53
	v_mov_b32_e32 v55, v107
	v_lshl_add_u64 v[110:111], s[14:15], 0, v[54:55]
	v_lshrrev_b32_e32 v54, 1, v175
	s_waitcnt vmcnt(24)
	v_bfe_u32 v66, v175, 2, 2
	v_and_or_b32 v54, v54, 24, v66
	v_mul_u32_u24_e32 v54, 0x108, v54
	s_lshl_b32 s21, s3, 5
	v_and_b32_e32 v66, 12, v52
	v_and_b32_e32 v58, 48, v174
	v_mov_b32_e32 v59, v107
	v_lshl_add_u64 v[112:113], s[14:15], 0, v[106:107]
	v_add3_u32 v54, v54, v66, s21
	s_add_i32 s14, 0, 0xce00
	v_lshrrev_b32_e32 v63, 4, v174
	v_lshl_add_u64 v[60:61], s[80:81], 0, v[58:59]
	s_mov_b64 s[6:7], 0x26a00000
	v_lshl_add_u32 v151, v54, 1, s14
	s_lshl_b32 s14, s3, 1
	s_lshr_b32 s22, s34, 7
	v_and_b32_e32 v62, 15, v175
	v_lshl_add_u64 v[108:109], v[60:61], 0, s[6:7]
	v_lshl_add_u32 v60, v53, 1, 0
	v_lshrrev_b32_e32 v53, 3, v175
	s_and_b32 s23, s14, 2
	s_lshl_b32 s14, s22, 4
	v_lshlrev_b32_e32 v66, 2, v63
	v_and_b32_e32 v55, 0x70, v53
	v_or_b32_e32 v67, s14, v66
	v_or_b32_e32 v54, s14, v62
	v_add_u32_e32 v114, 0, v58
	s_movk_i32 s14, 0x110
	s_waitcnt vmcnt(23)
	v_lshlrev_b32_e32 v69, 7, v62
	s_movk_i32 s24, 0x88
	v_or_b32_e32 v53, 15, v53
	v_mad_u64_u32 v[116:117], s[14:15], v54, s14, v[114:115]
	v_lshl_or_b32 v118, s3, 12, v69
	v_mul_u32_u24_e32 v69, 0x88, v126
	v_mad_u32_u24 v53, v53, s24, v115
	v_and_b32_e32 v54, 48, v175
	v_lshl_add_u32 v117, v69, 1, v60
	v_mul_u32_u24_e32 v69, 0x88, v127
	v_lshl_add_u32 v162, v53, 1, 0
	v_or_b32_e32 v53, 48, v174
	s_add_i32 s20, 0, 0x15200
	v_add_u32_e32 v58, 0, v54
	v_or_b32_e32 v54, s21, v62
	s_movk_i32 s21, 0x210
	v_lshl_add_u32 v152, v69, 1, v60
	v_mul_u32_u24_e32 v60, 0x108, v128
	v_mul_u32_u24_e32 v75, 0x90, v53
	v_mul_u32_u24_e32 v76, 0x110, v53
	v_or_b32_e32 v53, 48, v66
	v_mul_u32_u24_e32 v165, 0x840, v63
	v_mov_b32_e32 v63, 0xffff9f10
	v_add_u32_e32 v61, 0, v106
	v_add_u32_e32 v65, s20, v106
	v_lshlrev_b32_e32 v60, 1, v60
	s_movk_i32 s25, 0x4200
	v_mad_u32_u24 v166, v53, s21, v63
	v_mov_b32_e32 v63, 0xffffc430
	v_mov_b32_e32 v56, s64
	v_add_u32_e32 v153, v61, v60
	v_add3_u32 v158, v60, v65, s25
	v_mul_u32_u24_e32 v60, 0x108, v130
	v_lshlrev_b32_e32 v66, 1, v54
	v_mad_u32_u24 v167, v53, s21, v63
	v_mov_b32_e32 v63, 0x420
	s_load_dword s64, s[0:1], 0xa0
	v_mul_u32_u24_e32 v69, 0x108, v129
	v_lshlrev_b32_e32 v60, 1, v60
	v_mul_u32_u24_e32 v163, 0x210, v53
	v_mad_u32_u24 v168, v53, s21, v63
	v_or_b32_e32 v53, 32, v66
	s_lshl_b32 s38, s3, 8
	v_lshlrev_b32_e32 v69, 1, v69
	v_add_u32_e32 v159, v61, v60
	v_add_u32_e32 v160, v65, v60
	v_mul_u32_u24_e32 v55, 0x88, v55
	v_lshl_or_b32 v60, s23, 4, v62
	s_movk_i32 s24, 0x90
	v_add3_u32 v169, s20, v165, v53
	v_add3_u32 v170, s20, v166, v53
	v_add3_u32 v171, s20, v163, v53
	v_add3_u32 v180, s20, v167, v53
	v_add3_u32 v186, s20, v168, v53
	v_lshlrev_b32_e32 v52, 2, v52
	v_mov_b32_e32 v53, v107
	v_add_u32_e32 v154, v61, v69
	v_add_u32_e32 v155, v65, v69
	v_or_b32_e32 v156, 32, v128
	v_or_b32_e32 v55, v55, v115
	s_cmp_le_u32 s23, s22
	v_mul_lo_u32 v69, v67, s24
	v_lshl_add_u64 v[122:123], s[18:19], 0, v[52:53]
	v_lshl_add_u32 v52, v60, 1, 0
	v_mov_b32_e32 v57, s65
	v_add_u32_e32 v64, 0, v174
	v_lshlrev_b32_e32 v59, 4, v175
	s_movk_i32 s6, 0x80
	s_movk_i32 s8, 0xff
	s_movk_i32 s10, 0x17f
	s_movk_i32 s12, 0x1ff
	v_cmp_eq_u32_e64 s[14:15], 0, v62
	v_mul_u32_u24_e32 v68, 0x210, v128
	v_or_b32_e32 v120, 0x800, v118
	v_lshl_add_u32 v161, v55, 1, 0
	s_cselect_b64 s[48:49], -1, 0
	v_mul_u32_u24_e32 v61, 0x110, v60
	v_or_b32_e32 v70, 1, v67
	v_or_b32_e32 v71, 2, v67
	v_or_b32_e32 v72, 3, v67
	s_cmp_lt_u32 s23, s22
	v_or_b32_e32 v73, 16, v60
	v_mul_u32_u24_e32 v74, 0x90, v62
	v_mul_u32_u24_e32 v62, 0x110, v62
	v_mov_b32_e32 v55, v107
	v_add_u32_e32 v164, s20, v66
	v_mul_u32_u24_e32 v63, 0x210, v129
	v_mul_u32_u24_e32 v66, 0x210, v156
	v_mul_u32_u24_e32 v77, 0x210, v130
	v_add_u32_e32 v200, v52, v69
	v_mbcnt_lo_u32_b32 v52, -1, 0
	s_mov_b32 s47, 0
	v_lshl_add_u32 v149, v175, 2, 0
	v_lshl_add_u32 v150, v115, 2, 0
	v_cmp_gt_u32_e64 s[6:7], s6, v175
	v_cmp_lt_u32_e64 s[8:9], s8, v175
	v_cmp_lt_u32_e64 s[10:11], s10, v175
	v_cmp_lt_u32_e64 s[12:13], s12, v175
	v_cmp_gt_u32_e64 s[16:17], 64, v175
	v_ashrrev_i32_e32 v119, 31, v118
	v_ashrrev_i32_e32 v121, 31, v120
	v_add_u32_e32 v157, 0x4200, v153
	s_cselect_b64 s[50:51], -1, 0
	v_add_u32_e32 v172, 0xffffa120, v171
	v_add_u32_e32 v173, 0xffffa330, v171
	v_add_u32_e32 v177, 0xffffbe00, v171
	v_add_u32_e32 v178, 0xffffc010, v171
	v_add_u32_e32 v179, 0xffffc220, v171
	v_add_u32_e32 v181, 0xffffdf00, v171
	v_add_u32_e32 v182, 0xffffe110, v171
	v_add_u32_e32 v183, 0xffffe320, v171
	v_add_u32_e32 v184, 0xffffe530, v171
	v_add_u32_e32 v185, 0x210, v171
	v_add_u32_e32 v187, 0x210, v186
	v_cmp_gt_u32_e64 s[18:19], v60, v67
	v_cmp_gt_u32_e64 s[20:21], v60, v70
	v_cmp_gt_u32_e64 s[22:23], v60, v71
	v_cmp_gt_u32_e64 s[24:25], v60, v72
	v_cmp_gt_u32_e64 s[26:27], v73, v67
	v_cmp_gt_u32_e64 s[28:29], v73, v70
	v_cmp_gt_u32_e64 s[30:31], v73, v71
	v_cmp_gt_u32_e64 s[34:35], v73, v72
	v_lshl_add_u64 v[124:125], v[54:55], 2, v[56:57]
	s_waitcnt lgkmcnt(0)
	s_lshl_b32 s65, s64, 4
	s_lshl_b32 s67, s64, 6
	v_add_u32_e32 v188, 0, v59
	s_mov_b32 s72, 0xbfb8aa3b
	s_mov_b32 s73, 0x800000
	s_mov_b32 s76, 0x3f317217
	s_mov_b32 s77, 0x7f800000
	s_mov_b32 s84, 0x3d800000
	s_movk_i32 s85, 0x1000
	s_movk_i32 s86, 0x2000
	s_movk_i32 s87, 0x3000
	v_add_u32_e32 v189, v58, v74
	v_add_u32_e32 v190, v58, v75
	v_add_u32_e32 v191, v58, v62
	v_add_u32_e32 v192, v58, v76
	v_mov_b32_e32 v193, 0x358637bd
	s_mov_b32 s88, 0x6800000
	v_add_u32_e32 v194, v65, v63
	v_add_u32_e32 v195, v65, v66
	v_add_u32_e32 v196, v65, v77
	v_mov_b32_e32 v197, 0x41b17218
	v_add_u32_e32 v198, v65, v68
	v_add_u32_e32 v199, v114, v61
	v_mbcnt_hi_u32_b32 v201, -1, v52
	v_add_u32_e32 v202, s38, v64
	s_mov_b32 s52, s2
	global_load_dword v244, v[124:125], off
	global_load_dword v245, v[124:125], off offset:64
	s_branch .LBB0_423
; __device__ __forceinline__ unsigned pk2(float lo, float hi) { return pg8::cvt_pk_bf16_safe(lo, hi); }
; __device__ __forceinline__ float bf1(bf16 b) { return __uint_as_float(((unsigned)b) << 16); }
; __device__ __forceinline__ float silu_f(float v) { return v / (1.0f + __expf(-v)); }
; __device__ __forceinline__ void phase_g3(const Args& a, LAS unsigned char* lds, int tid, int lane, int wave) {
;     ...
;         for (int nt = 0; nt < 2; ++nt) { const int e = 32 * wave + 16 * nt + r16; const float gw = a.in[I_GNW][e];
; #pragma unroll
;             for (int mt = 0; mt < 4; ++mt)
; #pragma unroll
;                 for (int x = 0; x < 4; ++x) { const int i = 16 * mt + 4 * q4 + x; const float rr = bf1(Rs[i * 264 + e]);
;                     const float y = acc[mt][nt][x] * rstdL[i] * gw * silu_f(rr);
;                     Rs[i * 264 + e] = (bf16)(pk2(y, 0.f) & 0xffffu); } }
.LBB0_422:
	s_or_b64 exec, exec, s[38:39]
	s_waitcnt lgkmcnt(0)
	s_barrier
	v_add_u32_e32 v95, v164, v165
	ds_read_u16 v96, v95
	ds_read_b128 v[72:75], v114 offset:8256
	ds_read_b128 v[88:91], v114 offset:8192
	v_add_u32_e32 v94, v164, v166
	v_add_u32_e32 v97, v164, v163
	s_waitcnt lgkmcnt(2)
	v_lshlrev_b32_e32 v96, 16, v96
	v_mul_f32_e32 v98, 0xbfb8aa3b, v96
	v_exp_f32_e32 v98, v98
	s_waitcnt lgkmcnt(0)
	v_mul_f32_e32 v84, v84, v88
	v_mul_f32_e32 v85, v85, v89
	v_add_f32_e32 v98, 1.0, v98
	v_div_scale_f32 v99, s[38:39], v98, v98, v96
	v_rcp_f32_e32 v100, v99
	v_div_scale_f32 v101, vcc, v96, v98, v96
	v_mul_f32_e32 v86, v86, v90
	v_fma_f32 v102, -v99, v100, 1.0
	v_fmac_f32_e32 v100, v102, v100
	v_mul_f32_e32 v102, v101, v100
	v_fma_f32 v103, -v99, v102, v101
	v_fmac_f32_e32 v102, v103, v100
	v_fma_f32 v99, -v99, v102, v101
	v_div_fmas_f32 v99, v99, v100, v102
	v_div_fixup_f32 v96, v99, v98, v96
	v_mul_f32_e32 v80, v80, v72
	v_mul_f32_e32 v87, v87, v91
	v_mul_f32_e32 v83, v83, v75
	v_mul_f32_e32 v68, v68, v88
	v_mul_f32_e32 v69, v69, v89
	s_and_b32 s44, s58, 0xffffc000
	s_add_i32 s58, s58, s65
	s_waitcnt vmcnt(1)
	v_mul_f32_e32 v84, v244, v84
	v_mul_f32_e32 v84, v84, v96
	v_cvt_pk_bf16_f32 v84, v84, s0
	ds_write_b16 v95, v84
	ds_read_u16 v84, v94
	ds_read_u16 v95, v94 offset:528
	ds_read_u16 v96, v94 offset:1056
	ds_read_u16 v98, v94 offset:7920
	ds_read_u16 v99, v94 offset:8448
	ds_read_u16 v100, v94 offset:8976
	ds_read_u16 v101, v97
	s_waitcnt lgkmcnt(6)
	v_lshlrev_b32_e32 v84, 16, v84
	s_waitcnt lgkmcnt(5)
	v_lshlrev_b32_e32 v95, 16, v95
	v_mul_f32_e32 v102, 0xbfb8aa3b, v84
	s_waitcnt lgkmcnt(4)
	v_lshlrev_b32_e32 v96, 16, v96
	v_mul_f32_e32 v103, 0xbfb8aa3b, v95
	v_exp_f32_e32 v102, v102
	v_mul_f32_e32 v104, 0xbfb8aa3b, v96
	v_exp_f32_e32 v103, v103
	v_exp_f32_e32 v104, v104
	v_add_f32_e32 v102, 1.0, v102
	v_div_scale_f32 v203, s[38:39], v102, v102, v84
	v_add_f32_e32 v103, 1.0, v103
	v_add_f32_e32 v104, 1.0, v104
	v_div_scale_f32 v205, s[38:39], v103, v103, v95
	v_rcp_f32_e32 v208, v203
	v_div_scale_f32 v207, s[40:41], v104, v104, v96
	v_rcp_f32_e32 v209, v205
	v_rcp_f32_e32 v210, v207
	v_fma_f32 v212, -v203, v208, 1.0
	v_div_scale_f32 v204, vcc, v84, v102, v84
	v_fma_f32 v213, -v205, v209, 1.0
	v_fmac_f32_e32 v208, v212, v208
	s_waitcnt lgkmcnt(3)
	v_lshlrev_b32_e32 v98, 16, v98
	v_div_scale_f32 v206, s[38:39], v95, v103, v95
	v_fma_f32 v214, -v207, v210, 1.0
	v_fmac_f32_e32 v209, v213, v209
	v_mul_f32_e32 v212, v204, v208
	v_mul_f32_e32 v105, 0xbfb8aa3b, v98
	v_div_scale_f32 v211, s[40:41], v96, v104, v96
	v_fmac_f32_e32 v210, v214, v210
	v_mul_f32_e32 v213, v206, v209
	v_fma_f32 v215, -v203, v212, v204
	v_exp_f32_e32 v105, v105
	v_mul_f32_e32 v214, v211, v210
	v_fma_f32 v216, -v205, v213, v206
	v_fmac_f32_e32 v212, v215, v208
	v_fma_f32 v217, -v207, v214, v211
	v_fmac_f32_e32 v213, v216, v209
	v_fma_f32 v203, -v203, v212, v204
	v_fmac_f32_e32 v214, v217, v210
	v_fma_f32 v204, -v205, v213, v206
	v_div_fmas_f32 v203, v203, v208, v212
	s_mov_b64 vcc, s[38:39]
	v_mul_f32_e32 v85, v244, v85
	v_fma_f32 v205, -v207, v214, v211
	v_div_fixup_f32 v84, v203, v102, v84
	v_div_fmas_f32 v102, v204, v209, v213
	s_mov_b64 vcc, s[40:41]
	v_mul_f32_e32 v86, v244, v86
	v_add_f32_e32 v105, 1.0, v105
	v_mul_f32_e32 v84, v85, v84
	v_div_fixup_f32 v85, v102, v103, v95
	v_div_fmas_f32 v95, v205, v210, v214
	v_mul_f32_e32 v85, v86, v85
	v_div_fixup_f32 v86, v95, v104, v96
	v_div_scale_f32 v95, s[38:39], v105, v105, v98
	v_rcp_f32_e32 v96, v95
	v_mul_f32_e32 v80, v244, v80
	v_mul_f32_e32 v87, v244, v87
	v_cvt_pk_bf16_f32 v84, v84, s0
	v_fma_f32 v102, -v95, v96, 1.0
	v_fmac_f32_e32 v96, v102, v96
	v_div_scale_f32 v102, vcc, v98, v105, v98
	v_mul_f32_e32 v103, v102, v96
	v_fma_f32 v104, -v95, v103, v102
	v_fmac_f32_e32 v103, v104, v96
	v_fma_f32 v95, -v95, v103, v102
	v_div_fmas_f32 v95, v95, v96, v103
	s_waitcnt lgkmcnt(2)
	v_lshlrev_b32_e32 v96, 16, v99
	v_mul_f32_e32 v99, 0xbfb8aa3b, v96
	v_exp_f32_e32 v99, v99
	v_div_fixup_f32 v95, v95, v105, v98
	v_mul_f32_e32 v80, v80, v95
	v_cvt_pk_bf16_f32 v80, v80, s0
	v_add_f32_e32 v95, 1.0, v99
	v_div_scale_f32 v98, s[38:39], v95, v95, v96
	v_rcp_f32_e32 v99, v98
	ds_write_b16 v94, v80 offset:7920
	v_mul_f32_e32 v80, v81, v73
	v_mul_f32_e32 v80, v244, v80
	v_fma_f32 v81, -v98, v99, 1.0
	v_fmac_f32_e32 v99, v81, v99
	v_div_scale_f32 v81, vcc, v96, v95, v96
	v_mul_f32_e32 v102, v81, v99
	v_fma_f32 v103, -v98, v102, v81
	v_fmac_f32_e32 v102, v103, v99
	v_fma_f32 v81, -v98, v102, v81
	s_waitcnt lgkmcnt(2)
	v_lshlrev_b32_e32 v98, 16, v100
	v_div_fmas_f32 v81, v81, v99, v102
	v_mul_f32_e32 v99, 0xbfb8aa3b, v98
	v_exp_f32_e32 v99, v99
	v_div_fixup_f32 v81, v81, v95, v96
	v_mul_f32_e32 v80, v80, v81
	v_cvt_pk_bf16_f32 v80, v80, s0
	v_add_f32_e32 v81, 1.0, v99
	v_div_scale_f32 v95, s[38:39], v81, v81, v98
	v_rcp_f32_e32 v96, v95
	ds_write_b16 v94, v80 offset:8448
	v_mul_f32_e32 v80, v82, v74
	v_mul_f32_e32 v80, v244, v80
	v_fma_f32 v82, -v95, v96, 1.0
	v_fmac_f32_e32 v96, v82, v96
	v_div_scale_f32 v82, vcc, v98, v81, v98
	v_mul_f32_e32 v99, v82, v96
	v_fma_f32 v100, -v95, v99, v82
	v_fmac_f32_e32 v99, v100, v96
	v_fma_f32 v82, -v95, v99, v82
	v_div_fmas_f32 v82, v82, v96, v99
	v_div_fixup_f32 v81, v82, v81, v98
	ds_write_b16 v94, v84
	v_cvt_pk_bf16_f32 v84, v85, s0
	v_mul_f32_e32 v85, v87, v86
	v_mul_f32_e32 v80, v80, v81
	ds_write_b16 v94, v84 offset:528
	v_cvt_pk_bf16_f32 v84, v85, s0
	v_cvt_pk_bf16_f32 v80, v80, s0
	ds_write_b16 v94, v84 offset:1056
	ds_write_b16 v94, v80 offset:8976
	v_add_u32_e32 v94, v164, v167
	ds_read_b128 v[84:87], v114 offset:8384
	ds_read_u16 v80, v94
	ds_read_u16 v81, v94 offset:6864
	ds_read_u16 v95, v94 offset:7392
	ds_read_u16 v96, v94 offset:7920
	ds_read_u16 v98, v94 offset:8448
	s_waitcnt lgkmcnt(4)
; __device__ __forceinline__ unsigned pk2(float lo, float hi) { return pg8::cvt_pk_bf16_safe(lo, hi); }
; __device__ __forceinline__ float bf1(bf16 b) { return __uint_as_float(((unsigned)b) << 16); }
; __device__ __forceinline__ float silu_f(float v) { return v / (1.0f + __expf(-v)); }
; __device__ __forceinline__ void phase_g3(const Args& a, LAS unsigned char* lds, int tid, int lane, int wave) {
;     ...
;         for (int nt = 0; nt < 2; ++nt) { const int e = 32 * wave + 16 * nt + r16; const float gw = a.in[I_GNW][e];
; #pragma unroll
;             for (int mt = 0; mt < 4; ++mt)
; #pragma unroll
;                 for (int x = 0; x < 4; ++x) { const int i = 16 * mt + 4 * q4 + x; const float rr = bf1(Rs[i * 264 + e]);
;                     const float y = acc[mt][nt][x] * rstdL[i] * gw * silu_f(rr);
;                     Rs[i * 264 + e] = (bf16)(pk2(y, 0.f) & 0xffffu); } }
	v_lshlrev_b32_e32 v80, 16, v80
	v_mul_f32_e32 v82, 0xbfb8aa3b, v80
	v_exp_f32_e32 v82, v82
	s_waitcnt lgkmcnt(2)
	v_lshlrev_b32_e32 v95, 16, v95
	v_mul_f32_e32 v105, 0xbfb8aa3b, v95
	v_exp_f32_e32 v105, v105
	v_add_f32_e32 v82, 1.0, v82
	v_div_scale_f32 v99, s[38:39], v82, v82, v80
	v_rcp_f32_e32 v100, v99
	v_add_f32_e32 v105, 1.0, v105
	s_waitcnt lgkmcnt(1)
	v_lshlrev_b32_e32 v96, 16, v96
	s_waitcnt lgkmcnt(0)
	v_lshlrev_b32_e32 v98, 16, v98
	v_fma_f32 v102, -v99, v100, 1.0
	v_fmac_f32_e32 v100, v102, v100
	v_div_scale_f32 v102, vcc, v80, v82, v80
	v_mul_f32_e32 v103, v102, v100
	v_fma_f32 v104, -v99, v103, v102
	v_fmac_f32_e32 v103, v104, v100
	v_fma_f32 v99, -v99, v103, v102
	v_lshlrev_b32_e32 v102, 16, v81
	v_mul_f32_e32 v81, 0xbfb8aa3b, v102
	v_exp_f32_e32 v81, v81
	v_div_fmas_f32 v99, v99, v100, v103
	v_div_fixup_f32 v80, v99, v82, v80
	v_lshlrev_b32_e32 v101, 16, v101
	v_add_f32_e32 v99, 1.0, v81
	v_div_scale_f32 v100, s[38:39], v99, v99, v102
	v_rcp_f32_e32 v103, v100
	v_mul_f32_e32 v83, v244, v83
	v_mul_f32_e32 v80, v83, v80
	v_cvt_pk_bf16_f32 v80, v80, s0
	v_fma_f32 v104, -v100, v103, 1.0
	v_fmac_f32_e32 v103, v104, v103
	v_div_scale_f32 v104, vcc, v102, v99, v102
	v_mul_f32_e32 v203, v104, v103
	v_fma_f32 v204, -v100, v203, v104
	v_fmac_f32_e32 v203, v204, v103
	v_div_scale_f32 v204, s[38:39], v105, v105, v95
	v_rcp_f32_e32 v205, v204
	v_fma_f32 v100, -v100, v203, v104
	v_mul_f32_e32 v104, 0xbfb8aa3b, v96
	v_exp_f32_e32 v104, v104
	v_div_fmas_f32 v100, v100, v103, v203
	v_fma_f32 v103, -v204, v205, 1.0
	v_fmac_f32_e32 v205, v103, v205
	v_div_scale_f32 v103, vcc, v95, v105, v95
	v_mul_f32_e32 v203, v103, v205
	v_fma_f32 v206, -v204, v203, v103
	v_add_f32_e32 v104, 1.0, v104
	v_fmac_f32_e32 v203, v206, v205
	v_div_scale_f32 v206, s[38:39], v104, v104, v96
	v_rcp_f32_e32 v207, v206
	v_fma_f32 v103, -v204, v203, v103
	v_mul_f32_e32 v204, 0xbfb8aa3b, v98
	v_exp_f32_e32 v204, v204
	v_div_fmas_f32 v103, v103, v205, v203
	v_fma_f32 v203, -v206, v207, 1.0
	v_fmac_f32_e32 v207, v203, v207
	v_div_scale_f32 v203, vcc, v96, v104, v96
	v_mul_f32_e32 v205, v203, v207
	v_fma_f32 v208, -v206, v205, v203
	v_add_f32_e32 v204, 1.0, v204
	v_fmac_f32_e32 v205, v208, v207
	v_div_scale_f32 v208, s[38:39], v204, v204, v98
	v_rcp_f32_e32 v209, v208
	v_fma_f32 v203, -v206, v205, v203
	v_div_fmas_f32 v203, v203, v207, v205
	v_mul_f32_e32 v207, 0xbfb8aa3b, v101
	v_fma_f32 v205, -v208, v209, 1.0
	v_exp_f32_e32 v207, v207
	v_fmac_f32_e32 v209, v205, v209
	v_div_scale_f32 v205, vcc, v98, v204, v98
	v_mul_f32_e32 v206, v205, v209
	v_fma_f32 v210, -v208, v206, v205
	v_fmac_f32_e32 v206, v210, v209
	v_add_f32_e32 v207, 1.0, v207
	v_fma_f32 v205, -v208, v206, v205
	v_div_scale_f32 v208, s[38:39], v207, v207, v101
	v_rcp_f32_e32 v210, v208
	v_div_fmas_f32 v205, v205, v209, v206
	ds_write_b16 v94, v80
	ds_read_b128 v[80:83], v114 offset:8320
	v_fma_f32 v206, -v208, v210, 1.0
	v_fmac_f32_e32 v210, v206, v210
	v_div_scale_f32 v206, vcc, v101, v207, v101
	v_mul_f32_e32 v209, v206, v210
	v_fma_f32 v211, -v208, v209, v206
	v_fmac_f32_e32 v209, v211, v210
	v_fma_f32 v206, -v208, v209, v206
	v_mul_f32_e32 v56, v56, v84
	v_div_fmas_f32 v206, v206, v210, v209
	v_mul_f32_e32 v56, v244, v56
	v_div_fixup_f32 v101, v206, v207, v101
	v_mul_f32_e32 v56, v56, v101
	v_cvt_pk_bf16_f32 v56, v56, s0
	ds_write_b16 v97, v56
	ds_read_u16 v56, v94 offset:15840
	s_waitcnt lgkmcnt(2)
	v_mul_f32_e32 v76, v76, v80
	v_mul_f32_e32 v76, v244, v76
	v_div_fixup_f32 v97, v100, v99, v102
	v_mul_f32_e32 v76, v76, v97
	v_cvt_pk_bf16_f32 v76, v76, s0
	ds_write_b16 v94, v76 offset:6864
	v_mul_f32_e32 v76, v77, v81
	v_mul_f32_e32 v76, v244, v76
	v_div_fixup_f32 v77, v103, v105, v95
	v_mul_f32_e32 v76, v76, v77
	v_cvt_pk_bf16_f32 v76, v76, s0
	ds_write_b16 v94, v76 offset:7392
	v_mul_f32_e32 v76, v78, v82
	v_mul_f32_e32 v76, v244, v76
	v_div_fixup_f32 v77, v203, v104, v96
	s_waitcnt lgkmcnt(2)
	v_lshlrev_b32_e32 v56, 16, v56
	v_mul_f32_e32 v76, v76, v77
	v_mul_f32_e32 v77, 0xbfb8aa3b, v56
	v_exp_f32_e32 v77, v77
	v_cvt_pk_bf16_f32 v76, v76, s0
	ds_write_b16 v94, v76 offset:7920
	v_mul_f32_e32 v76, v79, v83
	v_mul_f32_e32 v76, v244, v76
	v_div_fixup_f32 v78, v205, v204, v98
	v_add_f32_e32 v77, 1.0, v77
	v_mul_f32_e32 v76, v76, v78
	v_div_scale_f32 v78, s[38:39], v77, v77, v56
	v_rcp_f32_e32 v79, v78
	v_cvt_pk_bf16_f32 v76, v76, s0
	ds_write_b16 v94, v76 offset:8448
	v_mul_f32_e32 v57, v57, v85
	v_fma_f32 v76, -v78, v79, 1.0
	v_fmac_f32_e32 v79, v76, v79
	v_div_scale_f32 v76, vcc, v56, v77, v56
	v_mul_f32_e32 v95, v76, v79
	v_fma_f32 v96, -v78, v95, v76
	v_fmac_f32_e32 v95, v96, v79
	v_fma_f32 v76, -v78, v95, v76
	v_div_fmas_f32 v76, v76, v79, v95
	v_mul_f32_e32 v57, v244, v57
	v_div_fixup_f32 v56, v76, v77, v56
	v_mul_f32_e32 v56, v57, v56
	v_cvt_pk_bf16_f32 v56, v56, s0
	ds_write_b16 v94, v56 offset:15840
	v_add_u32_e32 v56, v164, v168
	ds_read_u16 v57, v56
	ds_read_u16 v76, v56 offset:528
	v_mul_f32_e32 v58, v58, v86
	v_mul_f32_e32 v58, v244, v58
	s_waitcnt vmcnt(0)
	v_mul_f32_e32 v68, v68, v245
	s_waitcnt lgkmcnt(1)
	v_lshlrev_b32_e32 v57, 16, v57
	v_mul_f32_e32 v77, 0xbfb8aa3b, v57
	v_exp_f32_e32 v77, v77
	s_waitcnt lgkmcnt(0)
; __device__ __forceinline__ unsigned pk2(float lo, float hi) { return pg8::cvt_pk_bf16_safe(lo, hi); }
; __device__ __forceinline__ float bf1(bf16 b) { return __uint_as_float(((unsigned)b) << 16); }
; __device__ __forceinline__ float silu_f(float v) { return v / (1.0f + __expf(-v)); }
; __device__ __forceinline__ void phase_g3(const Args& a, LAS unsigned char* lds, int tid, int lane, int wave) {
;     ...
;         for (int nt = 0; nt < 2; ++nt) { const int e = 32 * wave + 16 * nt + r16; const float gw = a.in[I_GNW][e];
; #pragma unroll
;             for (int mt = 0; mt < 4; ++mt)
; #pragma unroll
;                 for (int x = 0; x < 4; ++x) { const int i = 16 * mt + 4 * q4 + x; const float rr = bf1(Rs[i * 264 + e]);
;                     const float y = acc[mt][nt][x] * rstdL[i] * gw * silu_f(rr);
;                     Rs[i * 264 + e] = (bf16)(pk2(y, 0.f) & 0xffffu); } }
	v_lshlrev_b32_e32 v76, 16, v76
	v_mul_f32_e32 v69, v69, v245
	v_mul_f32_e32 v60, v60, v80
	v_add_f32_e32 v77, 1.0, v77
	v_div_scale_f32 v78, s[38:39], v77, v77, v57
	v_rcp_f32_e32 v79, v78
	v_mul_f32_e32 v60, v60, v245
	v_mul_f32_e32 v62, v62, v82
	v_mul_f32_e32 v62, v62, v245
	v_fma_f32 v94, -v78, v79, 1.0
	v_fmac_f32_e32 v79, v94, v79
	v_div_scale_f32 v94, vcc, v57, v77, v57
	v_mul_f32_e32 v95, v94, v79
	v_fma_f32 v96, -v78, v95, v94
	v_fmac_f32_e32 v95, v96, v79
	v_fma_f32 v78, -v78, v95, v94
	v_div_fmas_f32 v78, v78, v79, v95
	v_mul_f32_e32 v79, 0xbfb8aa3b, v76
	v_exp_f32_e32 v79, v79
	v_div_fixup_f32 v57, v78, v77, v57
	v_mul_f32_e32 v57, v58, v57
	v_cvt_pk_bf16_f32 v57, v57, s0
	v_add_f32_e32 v58, 1.0, v79
	v_div_scale_f32 v77, s[38:39], v58, v58, v76
	v_rcp_f32_e32 v78, v77
	ds_write_b16 v56, v57
	v_mul_f32_e32 v57, v59, v87
	v_mul_f32_e32 v57, v244, v57
	v_fma_f32 v59, -v77, v78, 1.0
	v_fmac_f32_e32 v78, v59, v78
	v_div_scale_f32 v59, vcc, v76, v58, v76
	v_mul_f32_e32 v79, v59, v78
	v_fma_f32 v93, -v77, v79, v59
	v_fmac_f32_e32 v79, v93, v78
	v_fma_f32 v59, -v77, v79, v59
	v_div_fmas_f32 v59, v59, v78, v79
	v_div_fixup_f32 v58, v59, v58, v76
	v_mul_f32_e32 v57, v57, v58
	v_cvt_pk_bf16_f32 v57, v57, s0
	ds_write_b16 v56, v57 offset:528
	ds_read_u16 v56, v169
	v_mul_f32_e32 v52, v52, v84
	v_mul_f32_e32 v52, v52, v245
	v_mul_f32_e32 v53, v53, v85
	v_mul_f32_e32 v53, v53, v245
	s_waitcnt lgkmcnt(0)
	v_lshlrev_b32_e32 v56, 16, v56
	v_mul_f32_e32 v57, 0xbfb8aa3b, v56
	v_exp_f32_e32 v57, v57
	v_mul_f32_e32 v54, v54, v86
	v_mul_f32_e32 v54, v54, v245
	s_and_b32 s40, s59, 0x3fc0
	v_add_f32_e32 v57, 1.0, v57
	v_div_scale_f32 v58, s[38:39], v57, v57, v56
	v_rcp_f32_e32 v59, v58
	v_mul_f32_e32 v55, v55, v87
	v_mul_f32_e32 v55, v55, v245
	s_and_b32 s41, s52, 0x300
	v_fma_f32 v76, -v58, v59, 1.0
	v_fmac_f32_e32 v59, v76, v59
	v_div_scale_f32 v76, vcc, v56, v57, v56
	v_mul_f32_e32 v77, v76, v59
	v_fma_f32 v78, -v58, v77, v76
	v_fmac_f32_e32 v77, v78, v59
	v_fma_f32 v58, -v58, v77, v76
	v_div_fmas_f32 v58, v58, v59, v77
	v_div_fixup_f32 v56, v58, v57, v56
	v_mul_f32_e32 v56, v68, v56
	v_cvt_pk_bf16_f32 v56, v56, s0
	ds_write_b16 v169, v56
	ds_read_u16 v56, v170
	ds_read_u16 v57, v172
	ds_read_u16 v58, v173
	ds_read_u16 v59, v177
	ds_read_u16 v68, v178
	ds_read_u16 v76, v179
	ds_read_u16 v77, v171
	s_waitcnt lgkmcnt(6)
	v_lshlrev_b32_e32 v56, 16, v56
	v_mul_f32_e32 v78, 0xbfb8aa3b, v56
	v_exp_f32_e32 v78, v78
	s_waitcnt lgkmcnt(5)
	v_lshlrev_b32_e32 v57, 16, v57
	s_waitcnt lgkmcnt(4)
	v_lshlrev_b32_e32 v58, 16, v58
	s_waitcnt lgkmcnt(3)
	v_lshlrev_b32_e32 v59, 16, v59
	v_add_f32_e32 v78, 1.0, v78
	v_div_scale_f32 v79, s[38:39], v78, v78, v56
	v_rcp_f32_e32 v88, v79
	s_lshl_b32 s46, s41, 1
	s_add_i32 s59, s59, s67
	s_mov_b32 s52, s53
	v_fma_f32 v89, -v79, v88, 1.0
	v_fmac_f32_e32 v88, v89, v88
	v_div_scale_f32 v89, vcc, v56, v78, v56
	v_mul_f32_e32 v93, v89, v88
	v_fma_f32 v94, -v79, v93, v89
	v_fmac_f32_e32 v93, v94, v88
	v_fma_f32 v79, -v79, v93, v89
	v_div_fmas_f32 v79, v79, v88, v93
	v_mul_f32_e32 v88, 0xbfb8aa3b, v57
	v_exp_f32_e32 v88, v88
	v_div_fixup_f32 v56, v79, v78, v56
	v_mul_f32_e32 v56, v69, v56
	v_cvt_pk_bf16_f32 v56, v56, s0
	v_add_f32_e32 v69, 1.0, v88
	v_div_scale_f32 v78, s[38:39], v69, v69, v57
	v_rcp_f32_e32 v79, v78
	ds_write_b16 v170, v56
	v_mul_f32_e32 v56, v70, v90
	v_mul_f32_e32 v56, v56, v245
	v_fma_f32 v70, -v78, v79, 1.0
	v_fmac_f32_e32 v79, v70, v79
	v_div_scale_f32 v70, vcc, v57, v69, v57
	v_mul_f32_e32 v88, v70, v79
	v_fma_f32 v89, -v78, v88, v70
	v_fmac_f32_e32 v88, v89, v79
	v_fma_f32 v70, -v78, v88, v70
	v_mul_f32_e32 v78, 0xbfb8aa3b, v58
	v_exp_f32_e32 v78, v78
	v_div_fmas_f32 v70, v70, v79, v88
	v_div_fixup_f32 v57, v70, v69, v57
	v_mul_f32_e32 v56, v56, v57
	v_add_f32_e32 v57, 1.0, v78
	v_div_scale_f32 v69, s[38:39], v57, v57, v58
	v_rcp_f32_e32 v70, v69
	v_cvt_pk_bf16_f32 v56, v56, s0
	ds_write_b16 v172, v56
	v_mul_f32_e32 v56, v71, v91
	v_fma_f32 v71, -v69, v70, 1.0
	v_fmac_f32_e32 v70, v71, v70
	v_div_scale_f32 v71, vcc, v58, v57, v58
	v_mul_f32_e32 v78, v71, v70
	v_fma_f32 v79, -v69, v78, v71
	v_fmac_f32_e32 v78, v79, v70
	v_fma_f32 v69, -v69, v78, v71
	v_div_fmas_f32 v69, v69, v70, v78
	v_mul_f32_e32 v70, 0xbfb8aa3b, v59
	v_exp_f32_e32 v70, v70
	v_mul_f32_e32 v56, v56, v245
	v_div_fixup_f32 v57, v69, v57, v58
	v_mul_f32_e32 v56, v56, v57
	v_add_f32_e32 v57, 1.0, v70
	v_div_scale_f32 v58, s[38:39], v57, v57, v59
	v_rcp_f32_e32 v69, v58
	v_cvt_pk_bf16_f32 v56, v56, s0
	ds_write_b16 v173, v56
	v_mul_f32_e32 v56, v64, v72
	v_fma_f32 v64, -v58, v69, 1.0
	v_fmac_f32_e32 v69, v64, v69
	v_div_scale_f32 v64, vcc, v59, v57, v59
	v_mul_f32_e32 v70, v64, v69
	v_fma_f32 v71, -v58, v70, v64
	v_fmac_f32_e32 v70, v71, v69
	v_fma_f32 v58, -v58, v70, v64
	s_waitcnt lgkmcnt(5)
	v_lshlrev_b32_e32 v64, 16, v68
	v_mul_f32_e32 v68, 0xbfb8aa3b, v64
	v_exp_f32_e32 v68, v68
	v_div_fmas_f32 v58, v58, v69, v70
	v_mul_f32_e32 v56, v56, v245
	v_div_fixup_f32 v57, v58, v57, v59
	v_mul_f32_e32 v56, v56, v57
	v_add_f32_e32 v57, 1.0, v68
	v_div_scale_f32 v58, s[38:39], v57, v57, v64
	v_rcp_f32_e32 v59, v58
	v_cvt_pk_bf16_f32 v56, v56, s0
	ds_write_b16 v177, v56
	v_mul_f32_e32 v56, v65, v73
	v_fma_f32 v65, -v58, v59, 1.0
	v_fmac_f32_e32 v59, v65, v59
	v_div_scale_f32 v65, vcc, v64, v57, v64
	v_mul_f32_e32 v68, v65, v59
	v_fma_f32 v69, -v58, v68, v65
	v_fmac_f32_e32 v68, v69, v59
	v_fma_f32 v58, -v58, v68, v65
	v_div_fmas_f32 v58, v58, v59, v68
	s_waitcnt lgkmcnt(5)
; __device__ __forceinline__ unsigned pk2(float lo, float hi) { return pg8::cvt_pk_bf16_safe(lo, hi); }
; __device__ __forceinline__ float bf1(bf16 b) { return __uint_as_float(((unsigned)b) << 16); }
; __device__ __forceinline__ float silu_f(float v) { return v / (1.0f + __expf(-v)); }
; __device__ __forceinline__ void phase_g3(const Args& a, LAS unsigned char* lds, int tid, int lane, int wave) {
;     ...
;         for (int nt = 0; nt < 2; ++nt) { const int e = 32 * wave + 16 * nt + r16; const float gw = a.in[I_GNW][e];
; #pragma unroll
;             for (int mt = 0; mt < 4; ++mt)
; #pragma unroll
;                 for (int x = 0; x < 4; ++x) { const int i = 16 * mt + 4 * q4 + x; const float rr = bf1(Rs[i * 264 + e]);
;                     const float y = acc[mt][nt][x] * rstdL[i] * gw * silu_f(rr);
;                     Rs[i * 264 + e] = (bf16)(pk2(y, 0.f) & 0xffffu); } }
	v_lshlrev_b32_e32 v59, 16, v76
	v_mul_f32_e32 v65, 0xbfb8aa3b, v59
	v_exp_f32_e32 v65, v65
	v_mul_f32_e32 v56, v56, v245
	v_div_fixup_f32 v57, v58, v57, v64
	v_mul_f32_e32 v56, v56, v57
	v_add_f32_e32 v57, 1.0, v65
	v_div_scale_f32 v58, s[38:39], v57, v57, v59
	v_rcp_f32_e32 v64, v58
	v_cvt_pk_bf16_f32 v56, v56, s0
	ds_write_b16 v178, v56
	v_mul_f32_e32 v56, v66, v74
	v_fma_f32 v65, -v58, v64, 1.0
	v_fmac_f32_e32 v64, v65, v64
	v_div_scale_f32 v65, vcc, v59, v57, v59
	v_mul_f32_e32 v66, v65, v64
	v_fma_f32 v68, -v58, v66, v65
	v_fmac_f32_e32 v66, v68, v64
	v_fma_f32 v58, -v58, v66, v65
	v_div_fmas_f32 v58, v58, v64, v66
	v_mul_f32_e32 v56, v56, v245
	v_div_fixup_f32 v57, v58, v57, v59
	v_mul_f32_e32 v56, v56, v57
	v_cvt_pk_bf16_f32 v56, v56, s0
	ds_write_b16 v179, v56
	ds_read_u16 v56, v180
	ds_read_u16 v57, v183
	v_mul_f32_e32 v65, v67, v75
	v_mul_f32_e32 v65, v65, v245
	s_waitcnt lgkmcnt(1)
	v_lshlrev_b32_e32 v56, 16, v56
	v_mul_f32_e32 v58, 0xbfb8aa3b, v56
	v_exp_f32_e32 v58, v58
	s_waitcnt lgkmcnt(0)
	v_lshlrev_b32_e32 v57, 16, v57
	v_add_f32_e32 v58, 1.0, v58
	v_div_scale_f32 v59, s[38:39], v58, v58, v56
	v_rcp_f32_e32 v64, v59
	s_nop 0
	v_fma_f32 v66, -v59, v64, 1.0
	v_fmac_f32_e32 v64, v66, v64
	v_div_scale_f32 v66, vcc, v56, v58, v56
	v_mul_f32_e32 v67, v66, v64
	v_fma_f32 v68, -v59, v67, v66
	v_fmac_f32_e32 v67, v68, v64
	v_fma_f32 v59, -v59, v67, v66
	v_div_fmas_f32 v59, v59, v64, v67
	v_div_fixup_f32 v56, v59, v58, v56
	v_mul_f32_e32 v56, v65, v56
	v_cvt_pk_bf16_f32 v56, v56, s0
	ds_write_b16 v180, v56
	ds_read_u16 v56, v181
	ds_read_u16 v58, v182
	ds_read_u16 v59, v184
	s_waitcnt lgkmcnt(2)
	v_lshlrev_b32_e32 v56, 16, v56
	v_mul_f32_e32 v64, 0xbfb8aa3b, v56
	v_exp_f32_e32 v64, v64
	s_waitcnt lgkmcnt(1)
	v_lshlrev_b32_e32 v58, 16, v58
	v_mul_f32_e32 v69, 0xbfb8aa3b, v58
	v_exp_f32_e32 v69, v69
	v_add_f32_e32 v64, 1.0, v64
	v_div_scale_f32 v65, s[38:39], v64, v64, v56
	v_rcp_f32_e32 v66, v65
	s_waitcnt lgkmcnt(0)
	v_lshlrev_b32_e32 v59, 16, v59
	v_fma_f32 v67, -v65, v66, 1.0
	v_fmac_f32_e32 v66, v67, v66
	v_div_scale_f32 v67, vcc, v56, v64, v56
	v_mul_f32_e32 v68, v67, v66
	v_fma_f32 v70, -v65, v68, v67
	v_fmac_f32_e32 v68, v70, v66
	v_fma_f32 v65, -v65, v68, v67
	v_add_f32_e32 v67, 1.0, v69
	v_div_scale_f32 v69, s[38:39], v67, v67, v58
	v_rcp_f32_e32 v70, v69
	v_div_fmas_f32 v65, v65, v66, v68
	v_div_fixup_f32 v56, v65, v64, v56
	v_mul_f32_e32 v65, 0xbfb8aa3b, v57
	v_exp_f32_e32 v65, v65
	v_mul_f32_e32 v56, v60, v56
	v_fma_f32 v60, -v69, v70, 1.0
	v_fmac_f32_e32 v70, v60, v70
	v_div_scale_f32 v60, vcc, v58, v67, v58
	v_mul_f32_e32 v64, v60, v70
	v_fma_f32 v66, -v69, v64, v60
	v_add_f32_e32 v65, 1.0, v65
	v_fmac_f32_e32 v64, v66, v70
	v_div_scale_f32 v66, s[38:39], v65, v65, v57
	v_rcp_f32_e32 v68, v66
	v_fma_f32 v60, -v69, v64, v60
	v_div_fmas_f32 v60, v60, v70, v64
	v_cvt_pk_bf16_f32 v56, v56, s0
	v_fma_f32 v64, -v66, v68, 1.0
	v_fmac_f32_e32 v68, v64, v68
	v_div_scale_f32 v64, vcc, v57, v65, v57
	v_mul_f32_e32 v69, v64, v68
	v_fma_f32 v70, -v66, v69, v64
	v_fmac_f32_e32 v69, v70, v68
	v_fma_f32 v64, -v66, v69, v64
	v_mul_f32_e32 v66, 0xbfb8aa3b, v59
	v_exp_f32_e32 v66, v66
	v_div_fmas_f32 v64, v64, v68, v69
	v_div_fixup_f32 v57, v64, v65, v57
	v_mul_f32_e32 v57, v62, v57
	v_add_f32_e32 v62, 1.0, v66
	v_div_scale_f32 v64, s[38:39], v62, v62, v59
	v_rcp_f32_e32 v65, v64
	v_cvt_pk_bf16_f32 v57, v57, s0
	ds_write_b16 v183, v57
	v_mul_f32_e32 v57, v63, v83
	v_fma_f32 v63, -v64, v65, 1.0
	v_fmac_f32_e32 v65, v63, v65
	v_div_scale_f32 v63, vcc, v59, v62, v59
	v_mul_f32_e32 v66, v63, v65
	v_fma_f32 v68, -v64, v66, v63
	v_fmac_f32_e32 v66, v68, v65
	v_fma_f32 v63, -v64, v66, v63
	v_lshlrev_b32_e32 v64, 16, v77
	v_div_fmas_f32 v63, v63, v65, v66
	v_mul_f32_e32 v65, 0xbfb8aa3b, v64
	v_exp_f32_e32 v65, v65
	v_mul_f32_e32 v57, v57, v245
	v_div_fixup_f32 v59, v63, v62, v59
	v_mul_f32_e32 v57, v57, v59
	v_add_f32_e32 v59, 1.0, v65
	v_div_scale_f32 v62, s[38:39], v59, v59, v64
	v_rcp_f32_e32 v63, v62
	v_cvt_pk_bf16_f32 v57, v57, s0
	ds_write_b16 v184, v57
	ds_write_b16 v181, v56
	v_fma_f32 v57, -v62, v63, 1.0
	v_fmac_f32_e32 v63, v57, v63
	v_div_scale_f32 v57, vcc, v64, v59, v64
	v_mul_f32_e32 v65, v57, v63
	v_fma_f32 v66, -v62, v65, v57
	v_fmac_f32_e32 v65, v66, v63
	v_fma_f32 v57, -v62, v65, v57
	v_div_fmas_f32 v57, v57, v63, v65
	v_div_fixup_f32 v57, v57, v59, v64
	v_mul_f32_e32 v52, v52, v57
	v_cvt_pk_bf16_f32 v52, v52, s0
	ds_write_b16 v171, v52
	ds_read_u16 v52, v185
	v_mul_f32_e32 v56, v61, v81
	v_mul_f32_e32 v56, v56, v245
	v_div_fixup_f32 v58, v60, v67, v58
	v_mul_f32_e32 v56, v56, v58
	s_waitcnt lgkmcnt(0)
	v_lshlrev_b32_e32 v52, 16, v52
	v_mul_f32_e32 v57, 0xbfb8aa3b, v52
	v_exp_f32_e32 v57, v57
	v_cvt_pk_bf16_f32 v56, v56, s0
	ds_write_b16 v182, v56
	v_add_f32_e32 v57, 1.0, v57
	v_div_scale_f32 v58, s[38:39], v57, v57, v52
	v_rcp_f32_e32 v59, v58
	s_nop 0
	v_fma_f32 v56, -v58, v59, 1.0
	v_fmac_f32_e32 v59, v56, v59
	v_div_scale_f32 v56, vcc, v52, v57, v52
	v_mul_f32_e32 v60, v56, v59
	v_fma_f32 v61, -v58, v60, v56
	v_fmac_f32_e32 v60, v61, v59
	v_fma_f32 v56, -v58, v60, v56
	v_div_fmas_f32 v56, v56, v59, v60
	v_div_fixup_f32 v52, v56, v57, v52
	v_mul_f32_e32 v52, v53, v52
	v_cvt_pk_bf16_f32 v52, v52, s0
	ds_write_b16 v185, v52
	ds_read_u16 v52, v186
	s_waitcnt lgkmcnt(0)
	v_lshlrev_b32_e32 v52, 16, v52
	v_mul_f32_e32 v53, 0xbfb8aa3b, v52
	v_exp_f32_e32 v53, v53
	s_nop 0
	v_add_f32_e32 v53, 1.0, v53
	v_div_scale_f32 v56, s[38:39], v53, v53, v52
	v_rcp_f32_e32 v57, v56
	s_nop 0
	v_fma_f32 v58, -v56, v57, 1.0
	v_fmac_f32_e32 v57, v58, v57
	v_div_scale_f32 v58, vcc, v52, v53, v52
	v_mul_f32_e32 v59, v58, v57
	v_fma_f32 v60, -v56, v59, v58
	v_fmac_f32_e32 v59, v60, v57
	v_fma_f32 v56, -v56, v59, v58
	v_div_fmas_f32 v56, v56, v57, v59
	v_div_fixup_f32 v52, v56, v53, v52
	v_mul_f32_e32 v52, v54, v52
	v_cvt_pk_bf16_f32 v52, v52, s0
	ds_write_b16 v186, v52
	ds_read_u16 v52, v187
	s_waitcnt lgkmcnt(0)
	v_lshlrev_b32_e32 v52, 16, v52
	v_mul_f32_e32 v53, 0xbfb8aa3b, v52
	v_exp_f32_e32 v53, v53
	s_nop 0
	v_add_f32_e32 v53, 1.0, v53
	v_div_scale_f32 v54, s[38:39], v53, v53, v52
	v_rcp_f32_e32 v56, v54
	s_or_b32 s38, s44, s40
	v_fma_f32 v57, -v54, v56, 1.0
	v_fmac_f32_e32 v56, v57, v56
	v_div_scale_f32 v57, vcc, v52, v53, v52
	v_mul_f32_e32 v58, v57, v56
	v_fma_f32 v59, -v54, v58, v57
	v_fmac_f32_e32 v58, v59, v56
	v_fma_f32 v54, -v54, v58, v57
	v_div_fmas_f32 v54, v54, v56, v58
	v_div_fixup_f32 v52, v54, v53, v52
	v_or_b32_e32 v56, s38, v128
	v_mul_f32_e32 v52, v55, v52
	v_ashrrev_i32_e32 v57, 31, v56
	v_cvt_pk_bf16_f32 v52, v52, s0
	v_lshlrev_b64 v[56:57], 12, v[56:57]
	ds_write_b16 v187, v52
	s_waitcnt lgkmcnt(0)
	s_barrier
; #define LAS __attribute__((address_space(3)))
; __device__ __forceinline__ void phase_g3(const Args& a, LAS unsigned char* lds, int tid, int lane, int wave) {
;     ...
;         __syncthreads();
; #pragma unroll
;         for (int s4 = 0; s4 < 4; ++s4) { const int c = tid + 512 * s4; *(v4u*)(Y + (size_t)(m0 + (c >> 5)) * D + 1024 + h * 256 + 8 * (c & 31)) = *(const LAS v4u*)(Rs + (c >> 5) * 264 + 8 * (c & 31)); }
;         __syncthreads();
	ds_read_b128 v[52:55], v198
	v_lshl_add_u64 v[56:57], s[80:81], 0, v[56:57]
	v_lshl_add_u64 v[56:57], v[56:57], 0, s[46:47]
	v_lshl_add_u64 v[56:57], v[56:57], 0, v[106:107]
	v_add_co_u32_e32 v60, vcc, s88, v56
	s_nop 1
	v_addc_co_u32_e32 v61, vcc, 0, v57, vcc
	ds_read_b128 v[56:59], v194
	s_waitcnt lgkmcnt(1)
	global_store_dwordx4 v[60:61], v[52:55], off offset:2048
	s_nop 1
	v_or_b32_e32 v52, s38, v129
	v_ashrrev_i32_e32 v53, 31, v52
	v_lshlrev_b64 v[52:53], 12, v[52:53]
	v_lshl_add_u64 v[52:53], s[80:81], 0, v[52:53]
	v_lshl_add_u64 v[52:53], v[52:53], 0, s[46:47]
	v_lshl_add_u64 v[52:53], v[52:53], 0, v[106:107]
	v_add_co_u32_e32 v52, vcc, s88, v52
	s_nop 1
	v_addc_co_u32_e32 v53, vcc, 0, v53, vcc
	s_waitcnt lgkmcnt(0)
	global_store_dwordx4 v[52:53], v[56:59], off offset:2048
	ds_read_b128 v[52:55], v195
	s_nop 0
	v_or_b32_e32 v56, s38, v156
	v_ashrrev_i32_e32 v57, 31, v56
	v_lshlrev_b64 v[56:57], 12, v[56:57]
	v_lshl_add_u64 v[56:57], s[80:81], 0, v[56:57]
	v_lshl_add_u64 v[56:57], v[56:57], 0, s[46:47]
	v_lshl_add_u64 v[56:57], v[56:57], 0, v[106:107]
	v_add_co_u32_e32 v60, vcc, s88, v56
	s_nop 1
	v_addc_co_u32_e32 v61, vcc, 0, v57, vcc
	ds_read_b128 v[56:59], v196
	s_waitcnt lgkmcnt(1)
	global_store_dwordx4 v[60:61], v[52:55], off offset:2048
	s_nop 1
	v_add_u32_e32 v52, s38, v130
	v_ashrrev_i32_e32 v53, 31, v52
	v_lshlrev_b64 v[52:53], 12, v[52:53]
	v_lshl_add_u64 v[52:53], s[80:81], 0, v[52:53]
	v_lshl_add_u64 v[52:53], v[52:53], 0, s[46:47]
	v_lshl_add_u64 v[52:53], v[52:53], 0, v[106:107]
	v_add_co_u32_e32 v52, vcc, 0x6800000, v52
	s_nop 1
	v_addc_co_u32_e32 v53, vcc, 0, v53, vcc
	s_andn2_b64 vcc, exec, s[56:57]
	s_waitcnt lgkmcnt(0)
	global_store_dwordx4 v[52:53], v[56:59], off offset:2048
	s_barrier
	s_cbranch_vccz .LBB0_467

; __device__ __forceinline__ void phase_g3(const Args& a, LAS unsigned char* lds, int tid, int lane, int wave) {
;     ...
; #pragma unroll
;         for (int mt = 0; mt < 4; ++mt)
; #pragma unroll
;             for (int x = 0; x < 4; ++x) { float ss = acc[mt][0][x] * acc[mt][0][x] + acc[mt][1][x] * acc[mt][1][x];
;                 ss += __shfl_xor(ss, 1); ss += __shfl_xor(ss, 2); ss += __shfl_xor(ss, 4); ss += __shfl_xor(ss, 8);
;                 if (r16 == 0) part[wave * 64 + 16 * mt + 4 * q4 + x] = ss; }
.LBB0_435:
	s_or_b64 exec, exec, s[38:39]
	v_mul_f32_e32 v88, v69, v69
	v_fmac_f32_e32 v88, v85, v85
	s_waitcnt lgkmcnt(0)
	s_waitcnt lgkmcnt(0)
	s_nop 1
	v_add_f32_dpp v88, v88, v88 quad_perm:[1,0,3,2] row_mask:0xf bank_mask:0xf
	s_nop 1
	v_add_f32_dpp v88, v88, v88 quad_perm:[2,3,0,1] row_mask:0xf bank_mask:0xf
	s_nop 1
	v_add_f32_dpp v88, v88, v88 row_half_mirror row_mask:0xf bank_mask:0xf
	s_nop 1
	v_add_f32_dpp v88, v88, v88 row_mirror row_mask:0xf bank_mask:0xf
	s_and_saveexec_b64 s[38:39], s[14:15]
	s_cbranch_execz .LBB0_437
	s_waitcnt lgkmcnt(0)
	ds_write_b32 v202, v88 offset:6148
.LBB0_437:
	s_or_b64 exec, exec, s[38:39]
	v_mul_f32_e32 v88, v70, v70
	v_fmac_f32_e32 v88, v86, v86
	s_waitcnt lgkmcnt(0)
	s_waitcnt lgkmcnt(0)
	s_nop 1
	v_add_f32_dpp v88, v88, v88 quad_perm:[1,0,3,2] row_mask:0xf bank_mask:0xf
	s_nop 1
	v_add_f32_dpp v88, v88, v88 quad_perm:[2,3,0,1] row_mask:0xf bank_mask:0xf
	s_nop 1
	v_add_f32_dpp v88, v88, v88 row_half_mirror row_mask:0xf bank_mask:0xf
	s_nop 1
	v_add_f32_dpp v88, v88, v88 row_mirror row_mask:0xf bank_mask:0xf
	s_and_saveexec_b64 s[38:39], s[14:15]
	s_cbranch_execz .LBB0_439
	s_waitcnt lgkmcnt(0)
	ds_write_b32 v202, v88 offset:6152
.LBB0_439:
	s_or_b64 exec, exec, s[38:39]
	v_mul_f32_e32 v88, v71, v71
	v_fmac_f32_e32 v88, v87, v87
	s_waitcnt lgkmcnt(0)
	s_waitcnt lgkmcnt(0)
	s_nop 1
	v_add_f32_dpp v88, v88, v88 quad_perm:[1,0,3,2] row_mask:0xf bank_mask:0xf
	s_nop 1
	v_add_f32_dpp v88, v88, v88 quad_perm:[2,3,0,1] row_mask:0xf bank_mask:0xf
	s_nop 1
	v_add_f32_dpp v88, v88, v88 row_half_mirror row_mask:0xf bank_mask:0xf
	s_nop 1
	v_add_f32_dpp v88, v88, v88 row_mirror row_mask:0xf bank_mask:0xf
	s_and_saveexec_b64 s[38:39], s[14:15]
	s_cbranch_execz .LBB0_441
	s_waitcnt lgkmcnt(0)
	ds_write_b32 v202, v88 offset:6156
.LBB0_441:
	s_or_b64 exec, exec, s[38:39]
	v_mul_f32_e32 v88, v64, v64
	v_fmac_f32_e32 v88, v80, v80
	s_waitcnt lgkmcnt(0)
	s_waitcnt lgkmcnt(0)
	s_nop 1
	v_add_f32_dpp v88, v88, v88 quad_perm:[1,0,3,2] row_mask:0xf bank_mask:0xf
	s_nop 1
	v_add_f32_dpp v88, v88, v88 quad_perm:[2,3,0,1] row_mask:0xf bank_mask:0xf
	s_nop 1
	v_add_f32_dpp v88, v88, v88 row_half_mirror row_mask:0xf bank_mask:0xf
	s_nop 1
	v_add_f32_dpp v88, v88, v88 row_mirror row_mask:0xf bank_mask:0xf
	s_and_saveexec_b64 s[38:39], s[14:15]
	s_cbranch_execz .LBB0_443
	s_waitcnt lgkmcnt(0)
	ds_write_b32 v202, v88 offset:6208
.LBB0_443:
	s_or_b64 exec, exec, s[38:39]
	v_mul_f32_e32 v88, v65, v65
	v_fmac_f32_e32 v88, v81, v81
	s_waitcnt lgkmcnt(0)
	s_waitcnt lgkmcnt(0)
	s_nop 1
	v_add_f32_dpp v88, v88, v88 quad_perm:[1,0,3,2] row_mask:0xf bank_mask:0xf
	s_nop 1
	v_add_f32_dpp v88, v88, v88 quad_perm:[2,3,0,1] row_mask:0xf bank_mask:0xf
	s_nop 1
	v_add_f32_dpp v88, v88, v88 row_half_mirror row_mask:0xf bank_mask:0xf
	s_nop 1
	v_add_f32_dpp v88, v88, v88 row_mirror row_mask:0xf bank_mask:0xf
	s_and_saveexec_b64 s[38:39], s[14:15]
	s_cbranch_execz .LBB0_445
	s_waitcnt lgkmcnt(0)
	ds_write_b32 v202, v88 offset:6212
.LBB0_445:
	s_or_b64 exec, exec, s[38:39]
	v_mul_f32_e32 v88, v66, v66
	v_fmac_f32_e32 v88, v82, v82
	s_waitcnt lgkmcnt(0)
	s_waitcnt lgkmcnt(0)
	s_nop 1
	v_add_f32_dpp v88, v88, v88 quad_perm:[1,0,3,2] row_mask:0xf bank_mask:0xf
	s_nop 1
	v_add_f32_dpp v88, v88, v88 quad_perm:[2,3,0,1] row_mask:0xf bank_mask:0xf
	s_nop 1
	v_add_f32_dpp v88, v88, v88 row_half_mirror row_mask:0xf bank_mask:0xf
	s_nop 1
	v_add_f32_dpp v88, v88, v88 row_mirror row_mask:0xf bank_mask:0xf
	s_and_saveexec_b64 s[38:39], s[14:15]
	s_cbranch_execz .LBB0_447
	s_waitcnt lgkmcnt(0)
	ds_write_b32 v202, v88 offset:6216
.LBB0_447:
	s_or_b64 exec, exec, s[38:39]
	v_mul_f32_e32 v88, v67, v67
	v_fmac_f32_e32 v88, v83, v83
	s_waitcnt lgkmcnt(0)
	s_waitcnt lgkmcnt(0)
	s_nop 1
	v_add_f32_dpp v88, v88, v88 quad_perm:[1,0,3,2] row_mask:0xf bank_mask:0xf
	s_nop 1
	v_add_f32_dpp v88, v88, v88 quad_perm:[2,3,0,1] row_mask:0xf bank_mask:0xf
	s_nop 1
	v_add_f32_dpp v88, v88, v88 row_half_mirror row_mask:0xf bank_mask:0xf
	s_nop 1
	v_add_f32_dpp v88, v88, v88 row_mirror row_mask:0xf bank_mask:0xf
	s_and_saveexec_b64 s[38:39], s[14:15]
	s_cbranch_execz .LBB0_449
	s_waitcnt lgkmcnt(0)
	ds_write_b32 v202, v88 offset:6220
; __device__ __forceinline__ void phase_g3(const Args& a, LAS unsigned char* lds, int tid, int lane, int wave) {
;     ...
; #pragma unroll
;         for (int mt = 0; mt < 4; ++mt)
; #pragma unroll
;             for (int x = 0; x < 4; ++x) { float ss = acc[mt][0][x] * acc[mt][0][x] + acc[mt][1][x] * acc[mt][1][x];
;                 ss += __shfl_xor(ss, 1); ss += __shfl_xor(ss, 2); ss += __shfl_xor(ss, 4); ss += __shfl_xor(ss, 8);
;                 if (r16 == 0) part[wave * 64 + 16 * mt + 4 * q4 + x] = ss; }
.LBB0_449:
	s_or_b64 exec, exec, s[38:39]
	v_mul_f32_e32 v88, v60, v60
	v_fmac_f32_e32 v88, v76, v76
	s_waitcnt lgkmcnt(0)
	s_waitcnt lgkmcnt(0)
	s_nop 1
	v_add_f32_dpp v88, v88, v88 quad_perm:[1,0,3,2] row_mask:0xf bank_mask:0xf
	s_nop 1
	v_add_f32_dpp v88, v88, v88 quad_perm:[2,3,0,1] row_mask:0xf bank_mask:0xf
	s_nop 1
	v_add_f32_dpp v88, v88, v88 row_half_mirror row_mask:0xf bank_mask:0xf
	s_nop 1
	v_add_f32_dpp v88, v88, v88 row_mirror row_mask:0xf bank_mask:0xf
	s_and_saveexec_b64 s[38:39], s[14:15]
	s_cbranch_execz .LBB0_451
	s_waitcnt lgkmcnt(0)
	ds_write_b32 v202, v88 offset:6272
.LBB0_451:
	s_or_b64 exec, exec, s[38:39]
	v_mul_f32_e32 v88, v61, v61
	v_fmac_f32_e32 v88, v77, v77
	s_waitcnt lgkmcnt(0)
	s_waitcnt lgkmcnt(0)
	s_nop 1
	v_add_f32_dpp v88, v88, v88 quad_perm:[1,0,3,2] row_mask:0xf bank_mask:0xf
	s_nop 1
	v_add_f32_dpp v88, v88, v88 quad_perm:[2,3,0,1] row_mask:0xf bank_mask:0xf
	s_nop 1
	v_add_f32_dpp v88, v88, v88 row_half_mirror row_mask:0xf bank_mask:0xf
	s_nop 1
	v_add_f32_dpp v88, v88, v88 row_mirror row_mask:0xf bank_mask:0xf
	s_and_saveexec_b64 s[38:39], s[14:15]
	s_cbranch_execz .LBB0_453
	s_waitcnt lgkmcnt(0)
	ds_write_b32 v202, v88 offset:6276
.LBB0_453:
	s_or_b64 exec, exec, s[38:39]
	v_mul_f32_e32 v88, v62, v62
	v_fmac_f32_e32 v88, v78, v78
	s_waitcnt lgkmcnt(0)
	s_waitcnt lgkmcnt(0)
	s_nop 1
	v_add_f32_dpp v88, v88, v88 quad_perm:[1,0,3,2] row_mask:0xf bank_mask:0xf
	s_nop 1
	v_add_f32_dpp v88, v88, v88 quad_perm:[2,3,0,1] row_mask:0xf bank_mask:0xf
	s_nop 1
	v_add_f32_dpp v88, v88, v88 row_half_mirror row_mask:0xf bank_mask:0xf
	s_nop 1
	v_add_f32_dpp v88, v88, v88 row_mirror row_mask:0xf bank_mask:0xf
	s_and_saveexec_b64 s[38:39], s[14:15]
	s_cbranch_execz .LBB0_455
	s_waitcnt lgkmcnt(0)
	ds_write_b32 v202, v88 offset:6280
.LBB0_455:
	s_or_b64 exec, exec, s[38:39]
	v_mul_f32_e32 v88, v63, v63
	v_fmac_f32_e32 v88, v79, v79
	s_waitcnt lgkmcnt(0)
	s_waitcnt lgkmcnt(0)
	s_nop 1
	v_add_f32_dpp v88, v88, v88 quad_perm:[1,0,3,2] row_mask:0xf bank_mask:0xf
	s_nop 1
	v_add_f32_dpp v88, v88, v88 quad_perm:[2,3,0,1] row_mask:0xf bank_mask:0xf
	s_nop 1
	v_add_f32_dpp v88, v88, v88 row_half_mirror row_mask:0xf bank_mask:0xf
	s_nop 1
	v_add_f32_dpp v88, v88, v88 row_mirror row_mask:0xf bank_mask:0xf
	s_and_saveexec_b64 s[38:39], s[14:15]
	s_cbranch_execz .LBB0_457
	s_waitcnt lgkmcnt(0)
	ds_write_b32 v202, v88 offset:6284
.LBB0_457:
	s_or_b64 exec, exec, s[38:39]
	v_mul_f32_e32 v88, v52, v52
	v_fmac_f32_e32 v88, v56, v56
	s_waitcnt lgkmcnt(0)
	s_waitcnt lgkmcnt(0)
	s_nop 1
	v_add_f32_dpp v88, v88, v88 quad_perm:[1,0,3,2] row_mask:0xf bank_mask:0xf
	s_nop 1
	v_add_f32_dpp v88, v88, v88 quad_perm:[2,3,0,1] row_mask:0xf bank_mask:0xf
	s_nop 1
	v_add_f32_dpp v88, v88, v88 row_half_mirror row_mask:0xf bank_mask:0xf
	s_nop 1
	v_add_f32_dpp v88, v88, v88 row_mirror row_mask:0xf bank_mask:0xf
	s_and_saveexec_b64 s[38:39], s[14:15]
	s_cbranch_execz .LBB0_459
	s_waitcnt lgkmcnt(0)
	ds_write_b32 v202, v88 offset:6336
.LBB0_459:
	s_or_b64 exec, exec, s[38:39]
	v_mul_f32_e32 v88, v53, v53
	v_fmac_f32_e32 v88, v57, v57
	s_waitcnt lgkmcnt(0)
	s_waitcnt lgkmcnt(0)
	s_nop 1
	v_add_f32_dpp v88, v88, v88 quad_perm:[1,0,3,2] row_mask:0xf bank_mask:0xf
	s_nop 1
	v_add_f32_dpp v88, v88, v88 quad_perm:[2,3,0,1] row_mask:0xf bank_mask:0xf
	s_nop 1
	v_add_f32_dpp v88, v88, v88 row_half_mirror row_mask:0xf bank_mask:0xf
	s_nop 1
	v_add_f32_dpp v88, v88, v88 row_mirror row_mask:0xf bank_mask:0xf
	s_and_saveexec_b64 s[38:39], s[14:15]
	s_cbranch_execz .LBB0_461
	s_waitcnt lgkmcnt(0)
	ds_write_b32 v202, v88 offset:6340
.LBB0_461:
	s_or_b64 exec, exec, s[38:39]
	v_mul_f32_e32 v88, v54, v54
	v_fmac_f32_e32 v88, v58, v58
	s_waitcnt lgkmcnt(0)
	s_waitcnt lgkmcnt(0)
	s_nop 1
	v_add_f32_dpp v88, v88, v88 quad_perm:[1,0,3,2] row_mask:0xf bank_mask:0xf
	s_nop 1
	v_add_f32_dpp v88, v88, v88 quad_perm:[2,3,0,1] row_mask:0xf bank_mask:0xf
	s_nop 1
	v_add_f32_dpp v88, v88, v88 row_half_mirror row_mask:0xf bank_mask:0xf
	s_nop 1
	v_add_f32_dpp v88, v88, v88 row_mirror row_mask:0xf bank_mask:0xf
	s_and_saveexec_b64 s[38:39], s[14:15]
	s_cbranch_execz .LBB0_463
	s_waitcnt lgkmcnt(0)
	ds_write_b32 v202, v88 offset:6344
.LBB0_463:
	s_or_b64 exec, exec, s[38:39]
	v_mul_f32_e32 v88, v55, v55
	v_fmac_f32_e32 v88, v59, v59
	s_waitcnt lgkmcnt(0)
	s_nop 1
	v_add_f32_dpp v72, v88, v88 quad_perm:[1,0,3,2] row_mask:0xf bank_mask:0xf
	s_nop 1
	v_add_f32_dpp v72, v72, v72 quad_perm:[2,3,0,1] row_mask:0xf bank_mask:0xf
	s_nop 1
	v_add_f32_dpp v72, v72, v72 row_half_mirror row_mask:0xf bank_mask:0xf
	s_nop 1
	v_add_f32_dpp v72, v72, v72 row_mirror row_mask:0xf bank_mask:0xf
	s_and_saveexec_b64 s[38:39], s[14:15]
	s_cbranch_execz .LBB0_465
	s_waitcnt lgkmcnt(0)
	ds_write_b32 v202, v72 offset:6348
